# windowed attention unit prologue: the first K/V tile loads are issued before the kernarg scalar load and its wait (one scalar round trip no longer delays them); on attention zero-hoist stack
# speedup vs baseline: 1.0059x; 1.0059x over previous
.LBB0_785:
	v_readfirstlane_b32 s69, v105
	s_ashr_i32 s71, s69, 6
	s_lshl_b32 s22, s71, 5
	s_and_b32 s68, s22, 32
	v_or_b32_e32 v2, s68, v111
	s_ashr_i32 s22, s69, 7
	v_lshlrev_b32_e32 v0, 12, v2
	v_lshl_add_u64 v[4:5], s[20:21], 0, v[0:1]
	s_lshl_b32 s20, s22, 6
	s_ashr_i32 s21, s20, 31
	v_lshl_add_u64 v[4:5], s[20:21], 1, v[4:5]
	v_lshlrev_b32_e32 v0, 1, v104
	s_mov_b64 s[24:25], s[0:1]
	v_lshl_add_u64 v[4:5], v[4:5], 0, v[0:1]
	global_load_dwordx4 v[80:83], v[4:5], off
	global_load_dwordx4 v[84:87], v[4:5], off offset:32
	global_load_dwordx4 v[88:91], v[4:5], off offset:64
	global_load_dwordx4 v[92:95], v[4:5], off offset:96
	v_lshl_add_u64 v[4:5], s[14:15], 0, v[106:107]
	global_load_dwordx4 v[96:99], v[4:5], off
	v_lshl_add_u64 v[4:5], s[16:17], 0, v[106:107]
	v_lshl_add_u64 v[8:9], s[16:17], 0, v[108:109]
	global_load_dwordx4 v[100:103], v[4:5], off
	global_load_dwordx4 v[8:11], v[8:9], off
	v_lshl_add_u64 v[4:5], s[14:15], 0, v[108:109]
	global_load_dwordx4 v[4:7], v[4:5], off
	s_load_dwordx2 s[24:25], s[24:25], 0x70
	s_waitcnt lgkmcnt(0)
	s_cmp_eq_u64 s[24:25], 0
	s_cselect_b64 s[20:21], -1, 0
	s_and_b64 vcc, exec, s[20:21]
	s_cbranch_vccnz .LBB0_787
	s_add_u32 s23, s24, s4
	s_addc_u32 s24, s25, s5
	s_and_b64 s[18:19], exec, s[18:19]
	s_cselect_b32 s18, 5, 2
	s_lshr_b32 s18, s34, s18
	s_lshl_b32 s18, s18, 4
	s_and_b32 s18, s18, 0x70
	s_add_u32 s25, s23, s18
	s_addc_u32 s24, s24, 0
	s_ashr_i32 s23, s22, 31
	s_lshl_b64 s[18:19], s[22:23], 2
	s_add_u32 s18, s25, s18
	s_addc_u32 s19, s24, s19
	global_load_dword v134, v1, s[18:19]
	v_mov_b32_e32 v117, v118
	s_branch .LBB0_788

.LBB0_788:
	v_add_u32_e32 v0, v122, v120
	s_cmp_lt_i32 s72, 3
	v_mov_b32_e32 v3, v1
	v_mov_b32_e32 v12, v1
	v_mov_b32_e32 v13, v1
	v_mov_b32_e32 v14, v1
	v_mov_b32_e32 v15, v1
	v_mov_b32_e32 v16, v1
	v_mov_b32_e32 v17, v1
	v_mov_b32_e32 v18, v1
	v_mov_b32_e32 v19, v1
	v_mov_b32_e32 v20, v1
	v_mov_b32_e32 v21, v1
	v_mov_b32_e32 v22, v1
	v_mov_b32_e32 v23, v1
	v_mov_b32_e32 v24, v1
	v_mov_b32_e32 v25, v1
	v_mov_b32_e32 v26, v1
	v_mov_b32_e32 v27, v1
	v_mov_b32_e32 v28, v1
	v_mov_b32_e32 v29, v1
	v_mov_b32_e32 v30, v1
	v_mov_b32_e32 v31, v1
	v_mov_b32_e32 v32, v1
	v_mov_b32_e32 v33, v1
	v_mov_b32_e32 v34, v1
	v_mov_b32_e32 v35, v1
	v_mov_b32_e32 v36, v1
	v_mov_b32_e32 v37, v1
	v_mov_b32_e32 v38, v1
	v_mov_b32_e32 v39, v1
	v_mov_b32_e32 v40, v1
	v_mov_b32_e32 v41, v1
	v_mov_b32_e32 v42, v1
	v_mov_b32_e32 v43, v1
	v_mov_b32_e32 v44, v1
	v_mov_b32_e32 v45, v1
	v_mov_b32_e32 v46, v1
	v_mov_b32_e32 v47, v1
	v_mov_b32_e32 v48, v1
	v_mov_b32_e32 v49, v1
	v_mov_b32_e32 v50, v1
	v_mov_b32_e32 v51, v1
	v_mov_b32_e32 v52, v1
	v_mov_b32_e32 v53, v1
	v_mov_b32_e32 v54, v1
	v_mov_b32_e32 v55, v1
	v_mov_b32_e32 v56, v1
	v_mov_b32_e32 v57, v1
	v_mov_b32_e32 v58, v1
	v_mov_b32_e32 v59, v1
	v_mov_b32_e32 v60, v1
	v_mov_b32_e32 v61, v1
	v_mov_b32_e32 v62, v1
	v_mov_b32_e32 v63, v1
	v_mov_b32_e32 v64, v1
	v_mov_b32_e32 v65, v1
	v_mov_b32_e32 v66, v1
	v_mov_b32_e32 v67, v1
	v_mov_b32_e32 v68, v1
	v_mov_b32_e32 v69, v1
	v_mov_b32_e32 v70, v1
	v_mov_b32_e32 v71, v1
	v_mov_b32_e32 v72, v1
	v_mov_b32_e32 v73, v1
	v_mov_b32_e32 v74, v1
	v_mov_b32_e32 v75, v1
	v_mov_b32_e32 v76, v1
	v_mov_b32_e32 v77, v1
	v_mov_b32_e32 v78, v1
	v_mov_b32_e32 v79, v1
	s_waitcnt vmcnt(0)
	v_mul_f32_e32 v134, 0x3fb8aa3b, v134
	ds_write_b128 v0, v[96:99]
	v_add_u32_e32 v0, v110, v120
	ds_write_b128 v0, v[100:103] offset:9216
	v_add_u32_e32 v0, v112, v120
	ds_write_b128 v0, v[4:7] offset:21504
	ds_write_b128 v133, v[8:11] offset:30720
	s_cbranch_scc1 .LBB0_790
	v_lshl_add_u64 v[4:5], s[14:15], 0, v[114:115]
	global_load_dwordx4 v[96:99], v[4:5], off
	v_lshl_add_u64 v[4:5], s[16:17], 0, v[114:115]
	global_load_dwordx4 v[100:103], v[4:5], off
